# MoBA gate dot product with 16 v_pk_fma_f32 on an accumulator pair (was 24 fmac + 4 pk_mul + 8 add serial chain); f32 FMA, summation order changed
# speedup vs baseline: 1.0037x; 1.0037x over previous
.LBB0_390:
	ds_read_b128 v[60:63], v54
	ds_read_b128 v[68:71], v54 offset:16
	ds_read_b128 v[72:75], v54 offset:64
	ds_read_b128 v[76:79], v54 offset:80
	ds_read_b128 v[80:83], v54 offset:128
	s_waitcnt lgkmcnt(4)
	v_pk_mul_f32 v[64:65], v[60:61], v[26:27]
	v_pk_fma_f32 v[64:65], v[62:63], v[28:29], v[64:65]
	s_waitcnt lgkmcnt(3)
	v_pk_fma_f32 v[64:65], v[68:69], v[30:31], v[64:65]
	v_pk_fma_f32 v[64:65], v[70:71], v[32:33], v[64:65]
	s_waitcnt lgkmcnt(2)
	v_pk_fma_f32 v[64:65], v[72:73], v[38:39], v[64:65]
	v_pk_fma_f32 v[64:65], v[74:75], v[40:41], v[64:65]
	s_waitcnt lgkmcnt(1)
	v_pk_fma_f32 v[64:65], v[76:77], v[42:43], v[64:65]
	v_pk_fma_f32 v[64:65], v[78:79], v[44:45], v[64:65]
	ds_read_b128 v[60:63], v54 offset:144
	ds_read_b128 v[68:71], v54 offset:192
	s_waitcnt lgkmcnt(2)
	v_pk_fma_f32 v[64:65], v[80:81], v[46:47], v[64:65]
	v_pk_fma_f32 v[64:65], v[82:83], v[48:49], v[64:65]
	s_waitcnt lgkmcnt(1)
	v_pk_fma_f32 v[64:65], v[60:61], v[50:51], v[64:65]
	v_pk_fma_f32 v[64:65], v[62:63], v[52:53], v[64:65]
	ds_read_b128 v[60:63], v54 offset:208
	s_lshl_b32 s50, 1, s49
	s_waitcnt lgkmcnt(1)
	v_pk_fma_f32 v[64:65], v[68:69], v[18:19], v[64:65]
	v_pk_fma_f32 v[64:65], v[70:71], v[20:21], v[64:65]
	s_waitcnt lgkmcnt(0)
	v_pk_fma_f32 v[64:65], v[60:61], v[22:23], v[64:65]
	v_pk_fma_f32 v[64:65], v[62:63], v[24:25], v[64:65]
	v_add_f32_e32 v36, v64, v65
	v_mov_b32_e32 v37, v36
	s_nop 1
	v_permlane32_swap_b32_e32 v36, v37
	v_add_f32_e32 v60, v36, v37
	v_mov_b32_e32 v37, s50
	v_cmp_gt_f32_e64 s[8:9], v60, v55
	v_cmp_gt_f32_e64 s[42:43], v60, v56
	v_cmp_gt_f32_e32 vcc, v60, v59
	s_add_i32 s49, s49, 1
	v_add_u32_e32 v54, 0x100, v54
	v_cndmask_b32_e32 v35, v35, v37, vcc
	v_med3_f32 v59, v60, v56, v59
	v_cndmask_b32_e64 v35, v35, v57, s[42:43]
	v_cndmask_b32_e64 v57, v57, v37, s[42:43]
	v_med3_f32 v56, v60, v55, v56
	v_cndmask_b32_e64 v57, v57, v58, s[8:9]
	v_cndmask_b32_e64 v58, v58, v37, s[8:9]
	v_max_f32_e32 v55, v55, v60
	s_cmp_lg_u32 s82, s49
	s_cbranch_scc1 .LBB0_390
	v_mov_b32_e32 v37, v58
	v_mov_b32_e32 v36, v57
	s_branch .LBB0_400
